# panel-local seams (before Q-proj, Wo, FFN2 gate-up): four owners of a row panel meet on a per-panel counter when they share an XCD (checked at run time, falls back to the grid barrier)
# speedup vs baseline: 1.0359x; 1.0163x over previous
; #define LAS __attribute__((address_space(3)))
; __device__ __forceinline__ unsigned xb_add(unsigned* p, unsigned v) { return __hip_atomic_fetch_add(p, v, __ATOMIC_RELAXED, __HIP_MEMORY_SCOPE_AGENT); }
; __device__ __forceinline__ unsigned xb_xcc_id() { return (unsigned)__builtin_amdgcn_s_getreg((3 << 11) | 20) & 0xFu; }
; __device__ __forceinline__ XcdBarrier xcd_barrier_post(unsigned* bar, volatile LAS unsigned* st) {
;     XcdBarrier b; b.bar = bar; b.x = xb_xcc_id(); b.st = st;
;     if (threadIdx.x == 0) (void)xb_add(&bar[XB_XCNT(b.x)], 1u);
;     return b;
; }
; __global__ void __launch_bounds__(NT, 2) hymba_fwd(Args args) {
;     ...
;     volatile LAS unsigned* MISC = (volatile LAS unsigned*)(lds + MISC_OFF);
;     if (tid < 16) MISC[tid] = 0u;
;     __syncthreads();
;     XcdBarrier xbar = xcd_barrier_post((unsigned*)(ws + WS_BAR), MISC);
.LBB0_4:
	s_or_b64 exec, exec, s[4:5]
	s_waitcnt lgkmcnt(0)
	s_barrier
	s_add_u32 s46, s48, 0x64000
	s_getreg_b32 s4, hwreg(HW_REG_XCC_ID, 0, 4)
	s_addc_u32 s47, s49, 0
	s_and_b32 s33, s4, 15
	v_cmp_eq_u32_e64 s[44:45], 0, v209
	s_and_saveexec_b64 s[4:5], s[44:45]
	s_cbranch_execz .LBB0_7
	s_mov_b64 s[6:7], exec
	v_mbcnt_lo_u32_b32 v0, s6, 0
	v_mbcnt_hi_u32_b32 v0, s7, v0
	v_cmp_eq_u32_e32 vcc, 0, v0
	s_and_b64 s[8:9], exec, vcc
	s_mov_b64 exec, s[8:9]
	s_cbranch_execz .LBB0_7
	s_lshl_b32 s8, s33, 8
	s_bcnt1_i32_b64 s6, s[6:7]
	v_mov_b32_e32 v0, s8
	v_mov_b32_e32 v1, s6
	global_atomic_add v0, v1, s[46:47] offset:1024
	s_lshl_b32 s8, s2, 2
	s_add_i32 s8, s8, 0x8000
	s_add_i32 s6, s33, 1
	v_mov_b32_e32 v0, s8
	v_mov_b32_e32 v1, s6
	global_atomic_add v0, v1, s[46:47]

; __device__ __forceinline__ unsigned xb_ld(unsigned* p)              { return __hip_atomic_load(p, __ATOMIC_RELAXED, __HIP_MEMORY_SCOPE_AGENT); }
; __device__ __forceinline__ unsigned xb_add(unsigned* p, unsigned v) { return __hip_atomic_fetch_add(p, v, __ATOMIC_RELAXED, __HIP_MEMORY_SCOPE_AGENT); }
; #define XB_SPIN(cond, bar) do { unsigned _sp = 0; while (cond) { __builtin_amdgcn_s_sleep(1); \
;     if ((++_sp & 255u) == 0u) { if (xb_ld(&(bar)[XB_TMO])) break; if (_sp > XB_SPIN_CAP) { atomicAdd(&(bar)[XB_TMO], 1u); break; } } } } while (0)
; __device__ __forceinline__ void xcd_barrier(const XcdBarrier& b) {
;     asm volatile("s_waitcnt vmcnt(0)" ::: "memory");
;     __syncthreads();
;     if (threadIdx.x == 0) {
;         unsigned* bar = b.bar;
;         __builtin_amdgcn_s_waitcnt(0);
;         unsigned nloc = b.st[0], nx = b.st[1];
;         if (nloc == 0u) { xcd_barrier_complete(bar, b.x, nloc, nx); b.st[0] = nloc; b.st[1] = nx; }
;         const unsigned old = xb_add(&bar[XB_XSUB(b.x)], 1u);
;         const unsigned gen = old / nloc;
;         if (old + 1u == (gen + 1u) * nloc) {
;             __builtin_amdgcn_fence(__ATOMIC_RELEASE, "agent");
;             asm volatile("s_waitcnt vmcnt(0)" ::: "memory");
;             const unsigned og = xb_add(&bar[XB_TOP], 1u);
;             const unsigned tg = og / nx;
;             if (og + 1u == (tg + 1u) * nx) xb_add(&bar[XB_TOPGEN], 1u);
;             else XB_SPIN(xb_ld(&bar[XB_TOPGEN]) == tg, bar);
;             __builtin_amdgcn_fence(__ATOMIC_ACQUIRE, "agent");
;             xb_add(&bar[XB_XGEN(b.x)], 1u);
;             asm volatile("s_waitcnt vmcnt(0)" ::: "memory");
;         } else {
;             XB_SPIN(xb_ld(&bar[XB_XGEN(b.x)]) == gen, bar);
;             __builtin_amdgcn_fence(__ATOMIC_ACQUIRE, "agent");
;             asm volatile("s_waitcnt vmcnt(0)" ::: "memory");
;         }
;     }
;     __syncthreads();
; }
.LBB0_292:
	s_cmp_gt_i32 s51, 2
	s_cselect_b64 s[4:5], -1, 0
	s_and_b64 s[6:7], s[14:15], s[4:5]
	s_andn2_b64 vcc, exec, s[6:7]
	s_cbranch_vccnz .LBB0_346
	s_cmp_eq_u64 s[44:45], 0
	s_cbranch_scc1 .Lgb0_drain
	s_mov_b64 s[8:9], exec
	s_mov_b64 exec, s[44:45]
	s_lshl_b32 s10, s33, 8
	s_add_u32 s12, s46, s10
	s_addc_u32 s13, s47, 0
	v_mov_b32_e32 v1, 0x23fc0
	ds_read2_b32 v[2:3], v1 offset1:1
	v_mov_b32_e32 v0, 0x10000
	global_load_dword v5, v0, s[12:13] sc1
	s_xor_b32 s14, s2, 64
	s_lshl_b32 s14, s14, 2
	s_add_i32 s14, s14, 0x8000
	v_mov_b32_e32 v6, s14
	global_load_dword v6, v6, s[46:47] sc1
	s_xor_b32 s14, s2, 128
	s_lshl_b32 s14, s14, 2
	s_add_i32 s14, s14, 0x8000
	v_mov_b32_e32 v7, s14
	global_load_dword v7, v7, s[46:47] sc1
	s_xor_b32 s14, s2, 192
	s_lshl_b32 s14, s14, 2
	s_add_i32 s14, s14, 0x8000
	v_mov_b32_e32 v8, s14
	global_load_dword v8, v8, s[46:47] sc1
	s_mov_b64 exec, s[8:9]
.Lgb0_drain:
	s_waitcnt vmcnt(0) lgkmcnt(0)
	s_barrier
	s_cmp_eq_u64 s[44:45], 0
	s_cbranch_scc1 .Lgb0_end
	s_mov_b64 exec, s[44:45]
	v_readfirstlane_b32 s17, v6
	v_readfirstlane_b32 s18, v7
	v_readfirstlane_b32 s19, v8
	s_add_i32 s14, s33, 1
	s_cmp_lg_u32 s17, s14
	s_cbranch_scc1 .Lgb0_mis
	s_cmp_lg_u32 s18, s14
	s_cbranch_scc1 .Lgb0_mis
	s_cmp_eq_u32 s19, s14
	s_cbranch_scc1 .Lgb0_same
.Lgb0_mis:
	v_mov_b32_e32 v6, 0x8800
	v_mov_b32_e32 v7, 1
	global_atomic_add v6, v7, s[46:47]
	s_waitcnt vmcnt(0)
.Lgb0_same:
	s_mov_b32 s19, 0
	v_readfirstlane_b32 s15, v2
	v_readfirstlane_b32 s16, v3
	v_readfirstlane_b32 s14, v5
	s_add_i32 s17, s100, -1
	s_mul_i32 s17, s17, s16
	s_cmp_ge_u32 s14, s17
	s_cbranch_scc1 .Lgb0_prev_ok

; __device__ __forceinline__ unsigned xb_ld(unsigned* p)              { return __hip_atomic_load(p, __ATOMIC_RELAXED, __HIP_MEMORY_SCOPE_AGENT); }
; __device__ __forceinline__ unsigned xb_add(unsigned* p, unsigned v) { return __hip_atomic_fetch_add(p, v, __ATOMIC_RELAXED, __HIP_MEMORY_SCOPE_AGENT); }
; #define XB_SPIN(cond, bar) do { unsigned _sp = 0; while (cond) { __builtin_amdgcn_s_sleep(1); \
;     if ((++_sp & 255u) == 0u) { if (xb_ld(&(bar)[XB_TMO])) break; if (_sp > XB_SPIN_CAP) { atomicAdd(&(bar)[XB_TMO], 1u); break; } } } } while (0)
; __device__ __forceinline__ void xcd_barrier(const XcdBarrier& b) {
;     ...
;             __builtin_amdgcn_fence(__ATOMIC_ACQUIRE, "agent");
;             xb_add(&bar[XB_XGEN(b.x)], 1u);
;             asm volatile("s_waitcnt vmcnt(0)" ::: "memory");
;         } else {
;             XB_SPIN(xb_ld(&bar[XB_XGEN(b.x)]) == gen, bar);
;             __builtin_amdgcn_fence(__ATOMIC_ACQUIRE, "agent");
;             asm volatile("s_waitcnt vmcnt(0)" ::: "memory");
;         }
.Lgb0_acq:
	v_mov_b32_e32 v6, 0x8800
	global_load_dword v6, v6, s[46:47] sc1
	buffer_inv sc1
	s_waitcnt vmcnt(0)
	v_readfirstlane_b32 s14, v6
	s_cmp_eq_u32 s14, 0
	s_cselect_b32 s14, 1, 0
	v_mov_b32_e32 v7, s14
	v_mov_b32_e32 v6, 0x23fc8
	ds_write_b32 v6, v7
	s_waitcnt lgkmcnt(0)

; __device__ __forceinline__ void panel_sync(unsigned* cnt, int pm, int wid, int lane) {
;     asm volatile("s_waitcnt vmcnt(0) lgkmcnt(0)" ::: "memory"); __builtin_amdgcn_s_barrier(); asm volatile("" ::: "memory");
;     if (wid == 0) {
;         if (lane == 0) { __builtin_amdgcn_fence(__ATOMIC_RELEASE, "agent"); asm volatile("s_waitcnt vmcnt(0)" ::: "memory"); __hip_atomic_fetch_add(cnt + 64 * pm, 1u, __ATOMIC_RELAXED, __HIP_MEMORY_SCOPE_AGENT); }
;         unsigned sp = 0;
;         while ((unsigned)__builtin_amdgcn_readfirstlane(__hip_atomic_load(cnt + 64 * pm, __ATOMIC_RELAXED, __HIP_MEMORY_SCOPE_AGENT)) < 4u) { __builtin_amdgcn_s_sleep(2); if (++sp > (1u << 22)) break; }
;         __builtin_amdgcn_fence(__ATOMIC_ACQUIRE, "agent");
;         asm volatile("s_waitcnt vmcnt(0)" ::: "memory");
;     }
;     asm volatile("" ::: "memory"); __builtin_amdgcn_s_barrier(); asm volatile("" ::: "memory");
; }
.LBB0_1035:
	s_cmp_gt_i32 s51, 8
	s_cselect_b64 s[4:5], -1, 0
	s_and_b64 s[6:7], s[8:9], s[4:5]
	s_andn2_b64 vcc, exec, s[6:7]
	s_cbranch_vccnz .LBB0_1089
	v_mov_b32_e32 v1, 0x23fc8
	ds_read_b32 v2, v1
	s_waitcnt lgkmcnt(0)
	v_readfirstlane_b32 s14, v2
	s_cmp_lg_u32 s14, 1
	s_cbranch_scc1 .Lgb5_full
	s_waitcnt vmcnt(0)
	s_barrier
	s_cmp_eq_u64 s[44:45], 0
	s_cbranch_scc1 .Lgb5_gend
	s_mov_b64 s[8:9], exec
	s_mov_b64 exec, s[44:45]
	s_and_b32 s10, s2, 63
	s_lshl_b32 s10, s10, 8
	s_add_u32 s12, s46, s10
	s_addc_u32 s13, s47, 0
	v_mov_b32_e32 v0, 0xc000
	v_mov_b32_e32 v1, 1
	global_atomic_add v0, v1, s[12:13]
	s_mov_b32 s19, 0
.Lgb5_gpoll:
	global_load_dword v4, v0, s[12:13] sc1
	s_waitcnt vmcnt(0)
	v_readfirstlane_b32 s14, v4
	s_cmp_ge_u32 s14, 4
	s_cbranch_scc1 .Lgb5_gacq
	s_sleep 1
	s_add_i32 s19, s19, 1
	s_cmp_lt_u32 s19, 20000
	s_cbranch_scc1 .Lgb5_gpoll
.Lgb5_gacq:
	buffer_inv sc1
	s_waitcnt vmcnt(0)
	s_mov_b64 exec, s[8:9]
.Lgb5_gend:
	s_barrier
	s_branch .Lgb5_after
.Lgb5_full:
	s_cmp_eq_u64 s[44:45], 0
	s_cbranch_scc1 .Lgb5_drain
	s_mov_b64 s[8:9], exec
	s_mov_b64 exec, s[44:45]
	s_lshl_b32 s10, s33, 8
	s_add_u32 s12, s46, s10
	s_addc_u32 s13, s47, 0
	v_mov_b32_e32 v1, 0x23fc0
	ds_read2_b32 v[2:3], v1 offset1:1
	v_mov_b32_e32 v0, 0x10000
	global_load_dword v5, v0, s[12:13] sc1
	s_mov_b64 exec, s[8:9]

; #define PG8_BAR __builtin_amdgcn_s_barrier()
; template <class Epi, class Sched, bool ALIGN_EPI = false, bool SP2 = false>
; __device__ __forceinline__ void gemm_phase(PG8_LAS unsigned char* lds, const Gemm g, const Sched& S, const Epi& E) {
;     const int tid = threadIdx.x, wid = __builtin_amdgcn_readfirstlane(tid >> 6), lane = tid & 63, wr = wid >> 2, wc = wid & 3, fr = lane & 15, fq = lane >> 4;
;     const int K = g.K, nt = K / BK;
;     unsigned voffA[2], voffB[2];
; #pragma unroll
;     for (int i = 0; i < 2; ++i) { int R, C; stage_rc(tid * 16 + i * 8192, R, C); const int Rb = Epi::PERM ? ((R & ~31) + perm32(R & 31)) : R;
;         voffA[i] = (unsigned)(R * K + C) * 2u; voffB[i] = (unsigned)(Rb * K + C) * 2u; }
;     const size_t kstep = (size_t)(BK * 2);
;     const size_t hstep = (size_t)HALF * K * 2;
;     const size_t tstep = 2 * hstep;
;     const unsigned ldsw = (unsigned)wid * 1024u;
;     const int aoff = lds_byte(wr * 64 + fr, fq * 8), boff = lds_byte(wc * 32 + fr, fq * 8);
;     ...
;     Unit cur, nxt; int ui = 0;
;     if (!S.next(0, cur)) return;
;     f32x4 acc[2][2][4][2];
; #pragma unroll
;     for (int a = 0; a < 2; ++a)
; #pragma unroll
;         for (int b = 0; b < 2; ++b)
; #pragma unroll
;             for (int m = 0; m < 4; ++m)
; #pragma unroll
;                 for (int n = 0; n < 2; ++n) acc[a][b][m][n] = (f32x4){0.f, 0.f, 0.f, 0.f};
;     bf16x8 At[4][2], B0[2][2], B1[2][2];
;     const char* cA = (const char*)g.A + (size_t)cur.pm * tstep; const char* cB = (const char*)g.Bt + (size_t)cur.pn * tstep;
;     S.a_ready(cur);
;     if constexpr (SP2) {
;         PG8_STAGE(PG8_SB(0, 0), cB, voffB); PG8_STAGE(PG8_SB(0, 1), cB + hstep, voffB); PG8_STAGE(PG8_SA(0, 0), cA, voffA); PG8_STAGE(PG8_SA(0, 1), cA + hstep, voffA);
;         if (wr == 1) PG8_BAR;
;         PG8_WAIT_V(2); PG8_BAR;
;         PG8_STAGE(PG8_SB(1, 0), cB + kstep, voffB); PG8_STAGE(PG8_SA(1, 0), cA + kstep, voffA); PG8_STAGE(PG8_SB(1, 1), cB + hstep + kstep, voffB);
;         PG8_WAIT_V(6); PG8_BAR;
;     } else {
; __global__ void __launch_bounds__(NT, 2) hymba_fwd(Args args) {
;     ...
;     if (IN(8)) _Pragma("unroll") for (int rep = 0; rep < NREP(8); ++rep) {
;         pg8::Gemm g{XB, (const bf16*)(ws + WS_WQ), M, D, D}; pg8::StaticOrder S; S.init(M, D, G, bx);
;         EpiAttn E{ws, ssq + 2 * M, nullptr}; pg8::gemm_phase<EpiAttn, pg8::StaticOrder, false, true>(lds, g, S, E);
.Lgb5_after:
.LBB0_1089:
	s_cmp_lt_i32 s50, 9
	s_cselect_b64 s[6:7], -1, 0
	s_and_b64 s[8:9], s[6:7], s[4:5]
	s_andn2_b64 vcc, exec, s[8:9]
	s_cbranch_vccnz .LBB0_1111
	s_cmpk_gt_i32 s2, 0xff
	v_readfirstlane_b32 s30, v209
	s_cbranch_scc1 .LBB0_1111
	v_lshlrev_b32_e32 v144, 4, v209
	s_waitcnt vmcnt(0)
	v_and_b32_e32 v0, 32, v209
	v_bfe_u32 v10, v209, 2, 4
	v_bitop3_b32 v8, v144, v0, 48 bitop3:0x6c
	v_and_b32_e32 v9, 64, v209
	s_waitcnt lgkmcnt(0)
	v_lshrrev_b32_e32 v1, 3, v209
	s_movk_i32 s4, 0x70
	s_add_u32 s35, s48, 0x1b00000
	v_or_b32_e32 v0, v8, v9
	v_and_or_b32 v1, v1, s4, v10
	v_add_u32_e32 v11, 0x2000, v144
	s_addc_u32 s36, s49, 0
	v_lshl_or_b32 v128, v1, 11, v0
	v_lshrrev_b32_e32 v1, 7, v11
	s_movk_i32 s4, 0xf0
	s_ashr_i32 s38, s2, 31
	v_and_or_b32 v1, v1, s4, v10
	s_lshr_b32 s4, s38, 29
	s_add_i32 s4, s2, s4
	s_and_b32 s6, s4, -8
	s_lshr_b32 s31, s30, 6
	s_sub_i32 s6, s2, s6
	s_lshr_b32 s5, s30, 8
	s_lshl_b32 s37, s31, 10
	s_lshl_b32 s10, s6, 5
	s_ashr_i32 s4, s4, 3
	s_mul_i32 s7, s6, 33
	s_cmp_lt_i32 s6, 0
	s_cselect_b32 s6, s7, s10
	s_add_i32 s4, s6, s4
	s_ashr_i32 s6, s4, 31
	s_lshr_b32 s6, s6, 27
	s_add_i32 s6, s4, s6
	s_ashr_i32 s7, s6, 5
	s_andn2_b32 s6, s6, 31
	s_sub_i32 s6, s4, s6
	s_bfe_i32 s4, s6, 0x80000
	s_bfe_u32 s4, s4, 0x3000c
	s_add_i32 s10, s6, s4
	s_bfe_i32 s4, s10, 0x80000
	s_and_b32 s10, s10, 0xf8
	s_sub_i32 s6, s6, s10
	s_lshl_b32 s7, s7, 3
	s_sext_i32_i16 s4, s4
	s_sext_i32_i8 s6, s6
	s_lshr_b32 s4, s4, 3
	s_add_i32 s10, s7, s6
	s_ashr_i32 s11, s10, 31
	s_bfe_i64 s[12:13], s[4:5], 0x100000
	s_lshl_b64 s[6:7], s[10:11], 19
	s_lshl_b64 s[12:13], s[12:13], 19
	s_add_u32 s24, s35, s12
	s_addc_u32 s25, s36, s13
	s_add_i32 s11, s37, 0
	s_add_i32 m0, s11, 0x10000
	v_lshl_or_b32 v130, v1, 11, v0
	global_load_lds_dwordx4 v128, s[24:25]
	s_add_i32 m0, s11, 0x12000
	s_add_u32 s12, s24, 0x40000
	global_load_lds_dwordx4 v130, s[24:25]
	s_addc_u32 s13, s25, 0
	s_add_i32 m0, s11, 0x14000
	v_mov_b32_e32 v129, 0
	global_load_lds_dwordx4 v128, s[12:13]
	s_add_i32 m0, s11, 0x16000
	v_mov_b32_e32 v131, v129
	global_load_lds_dwordx4 v130, s[12:13]
	s_add_u32 s12, s54, s6
	s_addc_u32 s13, s55, s7
	s_add_i32 s40, s11, 0x2000
	s_mov_b32 m0, s11
	s_add_u32 s6, s12, 0x40000
	global_load_lds_dwordx4 v128, s[12:13]
	s_mov_b32 m0, s40
	s_addc_u32 s7, s13, 0
	s_add_i32 s41, s11, 0x4000
	global_load_lds_dwordx4 v130, s[12:13]
	s_mov_b32 m0, s41
	s_add_i32 s42, s11, 0x6000
	global_load_lds_dwordx4 v128, s[6:7]
	s_mov_b32 m0, s42
	s_mov_b32 s43, 0
	global_load_lds_dwordx4 v130, s[6:7]
	v_lshl_add_u64 v[6:7], s[24:25], 0, v[128:129]
	v_lshl_add_u64 v[4:5], s[24:25], 0, v[130:131]
	v_lshl_add_u64 v[2:3], s[12:13], 0, v[128:129]
	s_cmp_lg_u32 s5, 1
	v_lshl_add_u64 v[0:1], s[12:13], 0, v[130:131]
	s_cbranch_scc1 .LBB0_1093
	s_barrier

; __device__ __forceinline__ void panel_sync(unsigned* cnt, int pm, int wid, int lane) {
;     asm volatile("s_waitcnt vmcnt(0) lgkmcnt(0)" ::: "memory"); __builtin_amdgcn_s_barrier(); asm volatile("" ::: "memory");
;     if (wid == 0) {
;         if (lane == 0) { __builtin_amdgcn_fence(__ATOMIC_RELEASE, "agent"); asm volatile("s_waitcnt vmcnt(0)" ::: "memory"); __hip_atomic_fetch_add(cnt + 64 * pm, 1u, __ATOMIC_RELAXED, __HIP_MEMORY_SCOPE_AGENT); }
;         unsigned sp = 0;
;         while ((unsigned)__builtin_amdgcn_readfirstlane(__hip_atomic_load(cnt + 64 * pm, __ATOMIC_RELAXED, __HIP_MEMORY_SCOPE_AGENT)) < 4u) { __builtin_amdgcn_s_sleep(2); if (++sp > (1u << 22)) break; }
;         __builtin_amdgcn_fence(__ATOMIC_ACQUIRE, "agent");
;         asm volatile("s_waitcnt vmcnt(0)" ::: "memory");
;     }
;     asm volatile("" ::: "memory"); __builtin_amdgcn_s_barrier(); asm volatile("" ::: "memory");
; }
.LBB0_1111:
	s_cmp_gt_u32 s51, 9
	s_cselect_b64 s[4:5], -1, 0
	s_and_b64 s[4:5], s[8:9], s[4:5]
	s_andn2_b64 vcc, exec, s[4:5]
	s_cbranch_vccnz .LBB0_1165
	v_mov_b32_e32 v1, 0x23fc8
	ds_read_b32 v2, v1
	s_waitcnt lgkmcnt(0)
	v_readfirstlane_b32 s14, v2
	s_cmp_lg_u32 s14, 1
	s_cbranch_scc1 .Lgb6_full
	s_waitcnt vmcnt(0)
	s_barrier
	s_cmp_eq_u64 s[44:45], 0
	s_cbranch_scc1 .Lgb6_gend
	s_mov_b64 s[8:9], exec
	s_mov_b64 exec, s[44:45]
	s_and_b32 s10, s2, 63
	s_lshl_b32 s10, s10, 8
	s_add_u32 s12, s46, s10
	s_addc_u32 s13, s47, 0
	v_mov_b32_e32 v0, 0xc000
	v_mov_b32_e32 v1, 1
	global_atomic_add v0, v1, s[12:13]
	s_mov_b32 s19, 0
.Lgb6_gpoll:
	global_load_dword v4, v0, s[12:13] sc1
	s_waitcnt vmcnt(0)
	v_readfirstlane_b32 s14, v4
	s_cmp_ge_u32 s14, 8
	s_cbranch_scc1 .Lgb6_gacq
	s_sleep 1
	s_add_i32 s19, s19, 1
	s_cmp_lt_u32 s19, 20000
	s_cbranch_scc1 .Lgb6_gpoll

;     __host__ __device__ bool next(int i, Unit& u) const {
;         const long L = (long)i * G + c; if (L >= nwg) return false;
;         int wgid = (int)L; { const int q = nwg / NXCD, r = nwg % NXCD, xcd = wgid % NXCD, off = wgid / NXCD; wgid = (xcd < r ? xcd * (q + 1) : r * (q + 1) + (xcd - r) * q) + off; }
;         const int nig = WGM * nN, gid = wgid / nig, fm = gid * WGM, gsz = (nM - fm) < WGM ? (nM - fm) : WGM;
;         u.pm = fm + ((wgid % nig) % gsz); u.pn = (wgid % nig) / gsz; return true;
; __global__ void __launch_bounds__(NT, 2) hymba_fwd(Args args) {
;     ...
;     if (IN(10)) {
;         pg8::Gemm g{(const bf16*)(ws + WS_O), (const bf16*)(ws + WS_WO), M, D, D}; pg8::StaticOrder S; S.init(M, D, G, bx);
;         pg8::EpiResid E{nullptr, XB, ssq + 3 * M, 1.f, nullptr}; pg8::gemm_phase<pg8::EpiResid, pg8::StaticOrder, false, true>(lds, g, S, E);
.Lgb6_after:
.LBB0_1165:
	s_cmp_lt_i32 s50, 11
	s_cselect_b64 s[4:5], -1, 0
	s_cmp_gt_i32 s51, 10
	s_cselect_b64 s[6:7], -1, 0
	s_and_b64 s[8:9], s[4:5], s[6:7]
	s_andn2_b64 vcc, exec, s[8:9]
	s_cbranch_vccnz .LBB0_1207
	s_cmpk_gt_i32 s2, 0xff
	v_readfirstlane_b32 s30, v209
	s_cbranch_scc1 .LBB0_1207
	s_ashr_i32 s31, s2, 31
	s_lshr_b32 s4, s31, 29
	s_add_i32 s6, s2, s4
	s_and_b32 s4, s6, -8
	s_sub_i32 s10, s2, s4
	s_cmp_gt_i32 s10, -1
	s_cbranch_scc0 .LBB0_1169
	s_lshl_b32 s7, s10, 5
	s_cbranch_execz .LBB0_1170
	s_branch .LBB0_1171

; __device__ __forceinline__ void panel_sync(unsigned* cnt, int pm, int wid, int lane) {
;     asm volatile("s_waitcnt vmcnt(0) lgkmcnt(0)" ::: "memory"); __builtin_amdgcn_s_barrier(); asm volatile("" ::: "memory");
;     if (wid == 0) {
;         if (lane == 0) { __builtin_amdgcn_fence(__ATOMIC_RELEASE, "agent"); asm volatile("s_waitcnt vmcnt(0)" ::: "memory"); __hip_atomic_fetch_add(cnt + 64 * pm, 1u, __ATOMIC_RELAXED, __HIP_MEMORY_SCOPE_AGENT); }
;         unsigned sp = 0;
;         while ((unsigned)__builtin_amdgcn_readfirstlane(__hip_atomic_load(cnt + 64 * pm, __ATOMIC_RELAXED, __HIP_MEMORY_SCOPE_AGENT)) < 4u) { __builtin_amdgcn_s_sleep(2); if (++sp > (1u << 22)) break; }
;         __builtin_amdgcn_fence(__ATOMIC_ACQUIRE, "agent");
;         asm volatile("s_waitcnt vmcnt(0)" ::: "memory");
;     }
;     asm volatile("" ::: "memory"); __builtin_amdgcn_s_barrier(); asm volatile("" ::: "memory");
; }
.LBB0_1207:
	s_cmp_gt_i32 s51, 11
	s_cselect_b64 s[4:5], -1, 0
	s_and_b64 s[6:7], s[8:9], s[4:5]
	s_andn2_b64 vcc, exec, s[6:7]
	s_cbranch_vccnz .LBB0_1261
	v_mov_b32_e32 v1, 0x23fc8
	ds_read_b32 v2, v1
	s_waitcnt lgkmcnt(0)
	v_readfirstlane_b32 s14, v2
	s_cmp_lg_u32 s14, 1
	s_cbranch_scc1 .Lgb7_full
	s_waitcnt vmcnt(0)
	s_barrier
	s_cmp_eq_u64 s[44:45], 0
	s_cbranch_scc1 .Lgb7_gend
	s_mov_b64 s[8:9], exec
	s_mov_b64 exec, s[44:45]
	s_and_b32 s10, s2, 63
	s_lshl_b32 s10, s10, 8
	s_add_u32 s12, s46, s10
	s_addc_u32 s13, s47, 0
	v_mov_b32_e32 v0, 0xc000
	v_mov_b32_e32 v1, 1
	global_atomic_add v0, v1, s[12:13]
	s_mov_b32 s19, 0
.Lgb7_gpoll:
	global_load_dword v4, v0, s[12:13] sc1
	s_waitcnt vmcnt(0)
	v_readfirstlane_b32 s14, v4
	s_cmp_ge_u32 s14, 12
	s_cbranch_scc1 .Lgb7_gacq
	s_sleep 1
	s_add_i32 s19, s19, 1
	s_cmp_lt_u32 s19, 20000
	s_cbranch_scc1 .Lgb7_gpoll

; template <class Epi, class Sched, bool ALIGN_EPI = false, bool SP2 = false>
; __device__ __forceinline__ void gemm_phase(PG8_LAS unsigned char* lds, const Gemm g, const Sched& S, const Epi& E) {
;     const int tid = threadIdx.x, wid = __builtin_amdgcn_readfirstlane(tid >> 6), lane = tid & 63, wr = wid >> 2, wc = wid & 3, fr = lane & 15, fq = lane >> 4;
;     const int K = g.K, nt = K / BK;
;     unsigned voffA[2], voffB[2];
; #pragma unroll
;     for (int i = 0; i < 2; ++i) { int R, C; stage_rc(tid * 16 + i * 8192, R, C); const int Rb = Epi::PERM ? ((R & ~31) + perm32(R & 31)) : R;
;         voffA[i] = (unsigned)(R * K + C) * 2u; voffB[i] = (unsigned)(Rb * K + C) * 2u; }
;     const size_t kstep = (size_t)(BK * 2);
;     const size_t hstep = (size_t)HALF * K * 2;
;     const size_t tstep = 2 * hstep;
;     const unsigned ldsw = (unsigned)wid * 1024u;
;     const int aoff = lds_byte(wr * 64 + fr, fq * 8), boff = lds_byte(wc * 32 + fr, fq * 8);
;     ...
;     Unit cur, nxt; int ui = 0;
;     if (!S.next(0, cur)) return;
;     f32x4 acc[2][2][4][2];
; #pragma unroll
;     for (int a = 0; a < 2; ++a)
; #pragma unroll
;         for (int b = 0; b < 2; ++b)
; #pragma unroll
;             for (int m = 0; m < 4; ++m)
; #pragma unroll
;                 for (int n = 0; n < 2; ++n) acc[a][b][m][n] = (f32x4){0.f, 0.f, 0.f, 0.f};
;     bf16x8 At[4][2], B0[2][2], B1[2][2];
;     const char* cA = (const char*)g.A + (size_t)cur.pm * tstep; const char* cB = (const char*)g.Bt + (size_t)cur.pn * tstep;
;     S.a_ready(cur);
;     if constexpr (SP2) {
;         PG8_STAGE(PG8_SB(0, 0), cB, voffB); PG8_STAGE(PG8_SB(0, 1), cB + hstep, voffB); PG8_STAGE(PG8_SA(0, 0), cA, voffA); PG8_STAGE(PG8_SA(0, 1), cA + hstep, voffA);
;         if (wr == 1) PG8_BAR;
;         PG8_WAIT_V(2); PG8_BAR;
;         PG8_STAGE(PG8_SB(1, 0), cB + kstep, voffB); PG8_STAGE(PG8_SA(1, 0), cA + kstep, voffA); PG8_STAGE(PG8_SB(1, 1), cB + hstep + kstep, voffB);
;         PG8_WAIT_V(6); PG8_BAR;
;     } else {
; __global__ void __launch_bounds__(NT, 2) hymba_fwd(Args args) {
;     ...
;     if (IN(11)) _Pragma("unroll") for (int rep = 0; rep < NREP(11); ++rep) {
;         pg8::Gemm g{XB, (const bf16*)(ws + WS_WGU2), M, 2 * FF, D}; pg8::StaticOrder S; S.init(M, 2 * FF, G, bx);
;         pg8::EpiSwiglu E{Hb, FF, ssq + 3 * M}; pg8::gemm_phase<pg8::EpiSwiglu, pg8::StaticOrder, true, true>(lds, g, S, E);
.Lgb7_after:
.LBB0_1261:
	s_cmp_lt_i32 s50, 12
	s_cselect_b64 s[6:7], -1, 0
	s_and_b64 s[14:15], s[6:7], s[4:5]
	s_andn2_b64 vcc, exec, s[14:15]
	s_cbranch_vccnz .LBB0_1356
	s_lshl_b32 s4, s2, 3
	s_add_i32 s40, s88, s4
	s_add_i32 s59, s40, 0x2c80
	s_cmpk_lt_i32 s40, 0x580
	s_cselect_b64 s[8:9], -1, 0
	s_and_b64 s[4:5], s[8:9], exec
	s_cselect_b32 s60, s59, 0x2c80
	s_cmpk_gt_i32 s60, 0xaff
	s_cselect_b64 s[4:5], -1, 0
	s_cmpk_gt_i32 s60, 0xeff
	s_cselect_b64 s[6:7], -1, 0
	s_waitcnt vmcnt(0)
	v_cndmask_b32_e64 v0, 0, 1, s[6:7]
	s_cmp_lg_u64 s[4:5], 0
	v_readfirstlane_b32 s6, v0
	s_addc_u32 s61, s6, 0
	s_add_i32 s4, s40, 0xfffffc00
	s_add_i32 s41, s40, 0x2880
	s_cmpk_lt_i32 s4, 0x580
	s_cselect_b64 s[22:23], -1, 0
	s_and_b64 s[4:5], s[22:23], exec
	s_cselect_b32 s42, s41, 0x2c80
	s_cmpk_gt_i32 s42, 0xaff
	s_cselect_b64 s[4:5], -1, 0
	s_cmpk_gt_i32 s42, 0xeff
	s_cselect_b64 s[6:7], -1, 0
	s_load_dwordx2 s[20:21], s[0:1], 0xb0
	v_cndmask_b32_e64 v0, 0, 1, s[6:7]
	s_cmp_lg_u64 s[4:5], 0
	v_readfirstlane_b32 s6, v0
	s_addc_u32 s43, s6, 0
	s_cmpk_gt_i32 s2, 0x57f
	v_readfirstlane_b32 s5, v209
	s_cbranch_scc1 .LBB0_1278
	v_lshrrev_b32_e32 v2, 1, v209
	v_and_b32_e32 v11, 24, v2
	v_lshrrev_b32_e32 v2, 5, v209
	v_and_b32_e32 v2, 4, v2
	v_bfe_u32 v3, v209, 2, 2
	v_lshlrev_b32_e32 v0, 4, v209
	s_waitcnt lgkmcnt(0)
	v_and_b32_e32 v1, 32, v209
	v_bfe_u32 v10, v209, 2, 4
	v_or3_b32 v2, v2, v3, v11
	v_lshrrev_b32_e32 v3, 3, v209
	s_movk_i32 s4, 0x70
	v_bitop3_b32 v8, v0, v1, 48 bitop3:0x6c
	v_and_b32_e32 v9, 64, v209
	v_and_or_b32 v4, v3, s4, v10
	s_movk_i32 s4, 0x60
	v_add_u32_e32 v12, 0x2000, v0
	s_add_u32 s62, s48, 0x2300000
	v_or_b32_e32 v1, v8, v9
	v_and_or_b32 v3, v3, s4, v2
	v_lshrrev_b32_e32 v0, 7, v12
	s_movk_i32 s4, 0xf0
	s_addc_u32 s63, s49, 0
	v_lshl_or_b32 v130, v3, 11, v1
	v_and_or_b32 v3, v0, s4, v10
	s_movk_i32 s4, 0xe0
	s_ashr_i32 s65, s2, 31
	v_and_or_b32 v0, v0, s4, v2
	s_lshr_b32 s4, s65, 29
	s_add_i32 s4, s2, s4
	s_lshr_b32 s16, s5, 6
	s_ashr_i32 s6, s4, 3
	s_and_b32 s4, s4, -8
	s_lshr_b32 s18, s5, 8
	s_lshl_b32 s64, s16, 10
	s_sub_i32 s4, s2, s4
	s_cmp_lt_i32 s4, 0
	s_movk_i32 s66, 0xb1
	s_cselect_b32 s7, s66, 0xb0
	s_mul_i32 s4, s4, s7
	s_add_i32 s4, s4, s6
	s_mul_hi_i32 s6, s4, 0x2e8ba2e9
	s_lshr_b32 s7, s6, 31
	s_ashr_i32 s6, s6, 5
	s_add_i32 s6, s6, s7
	s_lshl_b32 s7, s6, 3
	s_mulk_i32 s6, 0xb0
	s_sub_i32 s6, s4, s6
	s_sext_i32_i16 s4, s6
	s_bfe_u32 s4, s4, 0x3001c
	s_add_i32 s10, s6, s4
	s_sext_i32_i16 s4, s10
	s_and_b32 s10, s10, 0xfff8
	s_sub_i32 s6, s6, s10
	s_sext_i32_i16 s6, s6
	s_lshr_b32 s4, s4, 3
	s_add_i32 s6, s7, s6
	s_ashr_i32 s7, s6, 31
	s_bfe_i64 s[12:13], s[4:5], 0x100000
	s_lshl_b64 s[10:11], s[6:7], 19
	s_lshl_b64 s[12:13], s[12:13], 19
	s_add_u32 s36, s62, s12
	s_addc_u32 s37, s63, s13
	s_add_i32 s67, s64, 0
	s_add_i32 m0, s67, 0x10000
	v_lshl_or_b32 v134, v0, 11, v1
	global_load_lds_dwordx4 v130, s[36:37]
	s_add_i32 m0, s67, 0x12000
	s_add_u32 s12, s36, 0x40000
	global_load_lds_dwordx4 v134, s[36:37]
	s_addc_u32 s13, s37, 0
	s_add_i32 m0, s67, 0x14000
	v_lshl_or_b32 v128, v4, 11, v1
	global_load_lds_dwordx4 v130, s[12:13]
	s_add_i32 m0, s67, 0x16000
	s_add_u32 s34, s54, s10
	s_addc_u32 s35, s55, s11
	s_add_i32 s68, s67, 0x2000
	global_load_lds_dwordx4 v134, s[12:13]
	s_mov_b32 m0, s67
	s_add_u32 s10, s34, 0x40000
	v_lshl_or_b32 v132, v3, 11, v1
	global_load_lds_dwordx4 v128, s[34:35]
	s_mov_b32 m0, s68
	s_addc_u32 s11, s35, 0
	s_add_i32 s69, s67, 0x4000
	global_load_lds_dwordx4 v132, s[34:35]
	s_mov_b32 m0, s69
	s_add_i32 s70, s67, 0x6000
	global_load_lds_dwordx4 v128, s[10:11]
	s_mov_b32 m0, s70
	v_mov_b32_e32 v131, 0
	global_load_lds_dwordx4 v132, s[10:11]
	v_mov_b32_e32 v135, v131
	v_mov_b32_e32 v129, v131
	v_mov_b32_e32 v133, v131
	s_cmp_eq_u32 s18, 1
	v_lshl_add_u64 v[6:7], s[36:37], 0, v[130:131]
	v_lshl_add_u64 v[4:5], s[36:37], 0, v[134:135]
	v_lshl_add_u64 v[0:1], s[34:35], 0, v[128:129]
	s_cselect_b64 s[10:11], -1, 0
	s_cmp_lg_u32 s18, 1
	v_lshl_add_u64 v[2:3], s[34:35], 0, v[132:133]
	s_cbranch_scc1 .LBB0_1265
	s_barrier
